# lat-A attention: V^T fragments read by ds_read_b64 straight into fresh operand quads (no v_mov shuffles), 5 of 8 pairs
# speedup vs baseline: 1.0058x; 1.0058x over previous
.LBB0_225:
	v_sub_f32_e32 v4, v96, v1
	v_exp_f32_e32 v9, v4
	v_sub_f32_e32 v5, v97, v1
	v_exp_f32_e32 v10, v5
	v_sub_f32_e32 v5, v98, v1
	v_exp_f32_e32 v11, v5
	v_sub_f32_e32 v5, v99, v1
	v_exp_f32_e32 v13, v5
	v_sub_f32_e32 v5, v100, v1
	v_add_f32_e32 v4, 0, v9
	v_exp_f32_e32 v14, v5
	v_sub_f32_e32 v5, v101, v1
	v_add_f32_e32 v4, v10, v4
	v_exp_f32_e32 v15, v5
	v_sub_f32_e32 v5, v102, v1
	v_add_f32_e32 v4, v11, v4
	v_exp_f32_e32 v96, v5
	v_sub_f32_e32 v5, v103, v1
	v_add_f32_e32 v4, v13, v4
	v_exp_f32_e32 v97, v5
	v_sub_f32_e32 v5, v104, v1
	v_add_f32_e32 v4, v14, v4
	v_exp_f32_e32 v5, v5
	v_sub_f32_e32 v6, v105, v1
	v_add_f32_e32 v4, v15, v4
	v_exp_f32_e32 v6, v6
	v_sub_f32_e32 v7, v106, v1
	v_add_f32_e32 v4, v96, v4
	v_exp_f32_e32 v7, v7
	v_sub_f32_e32 v12, v107, v1
	v_add_f32_e32 v4, v97, v4
	v_exp_f32_e32 v12, v12
	v_sub_f32_e32 v98, v108, v1
	v_add_f32_e32 v4, v5, v4
	v_exp_f32_e32 v98, v98
	v_sub_f32_e32 v99, v109, v1
	v_add_f32_e32 v4, v6, v4
	v_exp_f32_e32 v99, v99
	v_sub_f32_e32 v100, v110, v1
	v_add_f32_e32 v4, v7, v4
	v_exp_f32_e32 v100, v100
	v_sub_f32_e32 v101, v111, v1
	v_add_f32_e32 v4, v12, v4
	v_exp_f32_e32 v101, v101
	v_add_f32_e32 v4, v98, v4
	v_add_f32_e32 v4, v99, v4
	v_add_f32_e32 v4, v100, v4
	v_add_f32_e32 v4, v101, v4
	v_add_f32_e32 v3, v3, v4
	v_cvt_pk_bf16_f32 v4, v5, v6
	v_cvt_pk_bf16_f32 v5, v7, v12
	v_cvt_pk_bf16_f32 v12, v9, v10
	v_sub_f32_e32 v9, v80, v159
	v_cvt_pk_bf16_f32 v13, v11, v13
	v_exp_f32_e32 v9, v9
	v_sub_f32_e32 v11, v81, v159
	v_exp_f32_e32 v11, v11
	v_sub_f32_e32 v80, v82, v159
	v_exp_f32_e32 v81, v80
	v_sub_f32_e32 v80, v83, v159
	v_exp_f32_e32 v82, v80
	v_sub_f32_e32 v80, v84, v159
	v_add_f32_e32 v10, 0, v9
	v_exp_f32_e32 v83, v80
	v_sub_f32_e32 v80, v85, v159
	v_add_f32_e32 v10, v11, v10
	v_exp_f32_e32 v84, v80
	v_sub_f32_e32 v80, v86, v159
	v_add_f32_e32 v10, v81, v10
	v_exp_f32_e32 v85, v80
	v_sub_f32_e32 v80, v87, v159
	v_add_f32_e32 v10, v82, v10
	v_exp_f32_e32 v86, v80
	v_sub_f32_e32 v80, v88, v159
	v_add_f32_e32 v10, v83, v10
	v_exp_f32_e32 v87, v80
	v_sub_f32_e32 v80, v89, v159
	v_add_f32_e32 v10, v84, v10
	v_exp_f32_e32 v88, v80
	v_sub_f32_e32 v80, v90, v159
	v_add_f32_e32 v10, v85, v10
	v_exp_f32_e32 v89, v80
	v_sub_f32_e32 v80, v91, v159
	v_add_f32_e32 v10, v86, v10
	v_exp_f32_e32 v90, v80
	v_sub_f32_e32 v80, v92, v159
	v_add_f32_e32 v10, v87, v10
	v_exp_f32_e32 v91, v80
	v_sub_f32_e32 v80, v93, v159
	v_add_f32_e32 v10, v88, v10
	v_exp_f32_e32 v92, v80
	v_sub_f32_e32 v80, v94, v159
	v_add_f32_e32 v10, v89, v10
	v_exp_f32_e32 v93, v80
	v_sub_f32_e32 v80, v95, v159
	v_add_f32_e32 v10, v90, v10
	v_exp_f32_e32 v94, v80
	v_add_f32_e32 v10, v91, v10
	v_add_f32_e32 v10, v92, v10
	v_add_f32_e32 v10, v93, v10
	v_add_f32_e32 v10, v94, v10
	v_add_f32_e32 v162, v8, v10
	v_cvt_pk_bf16_f32 v81, v81, v82
	v_cvt_pk_bf16_f32 v82, v83, v84
	v_cvt_pk_bf16_f32 v8, v87, v88
	v_lshl_add_u32 v84, v158, 1, v204
	v_lshl_add_u32 v88, v157, 1, v204
	v_cvt_pk_bf16_f32 v80, v9, v11
	v_cvt_pk_bf16_f32 v83, v85, v86
	v_cvt_pk_bf16_f32 v9, v89, v90
	v_cvt_pk_bf16_f32 v10, v91, v92
	ds_read_b64 v[222:223], v84 offset:8192
	ds_read_b64 v[226:227], v84 offset:12288
	ds_read_b64 v[224:225], v88 offset:8192
	ds_read_b64 v[228:229], v88 offset:12288
	v_cvt_pk_bf16_f32 v11, v93, v94
	v_cvt_pk_bf16_f32 v14, v14, v15
	v_cvt_pk_bf16_f32 v15, v96, v97
	s_waitcnt lgkmcnt(0)
	v_mfma_f32_32x32x16_bf16 v[64:79], v[222:225], v[12:15], v[64:79]
	v_cvt_pk_bf16_f32 v6, v98, v99
	v_cvt_pk_bf16_f32 v7, v100, v101
	s_add_i32 s40, s40, 1
	s_add_i32 s2, s41, 1
	s_cmp_lg_u32 s41, 2
	s_cselect_b32 s41, s2, 0
	s_mov_b64 s[2:3], 0x2000
	v_mfma_f32_32x32x16_bf16 v[32:47], v[222:225], v[80:83], v[32:47]
	v_lshl_add_u64 v[150:151], v[150:151], 0, s[22:23]
	v_lshl_add_u64 v[152:153], v[152:153], 0, s[2:3]
	s_cmp_lg_u32 s40, 3
	v_mfma_f32_32x32x16_bf16 v[48:63], v[226:229], v[12:15], v[48:63]
	v_lshl_add_u32 v12, v156, 1, v204
	ds_read2st64_b64 v[12:15], v12 offset0:16 offset1:24
	s_waitcnt lgkmcnt(0)
	v_mov_b32_e32 v84, v12
	v_mfma_f32_32x32x16_bf16 v[16:31], v[226:229], v[80:83], v[16:31]
	v_lshl_add_u32 v80, v155, 1, v204
	ds_read2st64_b64 v[80:83], v80 offset0:16 offset1:24
	v_mov_b32_e32 v85, v13
	s_waitcnt lgkmcnt(0)
	v_mov_b32_e32 v86, v80
	v_mov_b32_e32 v87, v81
	v_mov_b32_e32 v80, v14
	v_mov_b32_e32 v81, v15
	v_mfma_f32_32x32x16_bf16 v[64:79], v[84:87], v[4:7], v[64:79]
	v_mfma_f32_32x32x16_bf16 v[32:47], v[84:87], v[8:11], v[32:47]
	v_mfma_f32_32x32x16_bf16 v[48:63], v[80:83], v[4:7], v[48:63]
	v_mfma_f32_32x32x16_bf16 v[16:31], v[80:83], v[8:11], v[16:31]
	s_cbranch_scc0 .LBB0_236

.LBB0_232:
	v_sub_f32_e32 v4, v96, v1
	v_exp_f32_e32 v4, v4
	v_sub_f32_e32 v6, v97, v1
	v_exp_f32_e32 v6, v6
	v_sub_f32_e32 v7, v98, v1
	v_exp_f32_e32 v7, v7
	v_sub_f32_e32 v8, v99, v1
	v_exp_f32_e32 v8, v8
	v_add_f32_e32 v5, 0, v4
	v_add_f32_e32 v5, v6, v5
	v_add_f32_e32 v5, v7, v5
	v_add_f32_e32 v5, v8, v5
	v_cvt_pk_bf16_f32 v97, v7, v8
	v_sub_f32_e32 v8, v80, v159
	v_exp_f32_e32 v207, v8
	v_sub_f32_e32 v8, v81, v159
	v_exp_f32_e32 v209, v8
	v_sub_f32_e32 v8, v82, v159
	v_exp_f32_e32 v210, v8
	v_sub_f32_e32 v8, v83, v159
	v_exp_f32_e32 v211, v8
	v_sub_f32_e32 v8, v84, v159
	v_exp_f32_e32 v212, v8
	v_sub_f32_e32 v8, v85, v159
	v_exp_f32_e32 v213, v8
	v_sub_f32_e32 v8, v86, v159
	v_exp_f32_e32 v214, v8
	v_sub_f32_e32 v8, v87, v159
	v_exp_f32_e32 v215, v8
	v_sub_f32_e32 v8, v88, v159
	v_exp_f32_e32 v216, v8
	v_sub_f32_e32 v8, v89, v159
	v_lshl_add_u32 v204, v154, 1, v204
	v_exp_f32_e32 v217, v8
	v_sub_f32_e32 v8, v90, v159
	v_lshl_add_u32 v84, v164, 1, v204
	v_lshl_add_u32 v88, v163, 1, v204
	v_exp_f32_e32 v218, v8
	v_sub_f32_e32 v8, v91, v159
	ds_read_b64 v[222:223], v84 offset:8192
	ds_read_b64 v[226:227], v84 offset:12288
	ds_read_b64 v[224:225], v88 offset:8192
	ds_read_b64 v[228:229], v88 offset:12288
	v_exp_f32_e32 v219, v8
	v_sub_f32_e32 v8, v92, v159
	v_sub_f32_e32 v9, v100, v1
	v_sub_f32_e32 v96, v103, v1
	v_exp_f32_e32 v220, v8
	v_sub_f32_e32 v8, v93, v159
	v_exp_f32_e32 v9, v9
	v_sub_f32_e32 v10, v101, v1
	v_exp_f32_e32 v99, v96
	v_sub_f32_e32 v96, v104, v1
	v_exp_f32_e32 v205, v8
	v_sub_f32_e32 v8, v94, v159
	v_exp_f32_e32 v10, v10
	v_sub_f32_e32 v11, v102, v1
	v_exp_f32_e32 v100, v96
	v_sub_f32_e32 v96, v105, v1
	v_exp_f32_e32 v206, v8
	v_sub_f32_e32 v8, v95, v159
	s_waitcnt lgkmcnt(0)
	v_exp_f32_e32 v11, v11
	v_exp_f32_e32 v101, v96
	v_sub_f32_e32 v96, v106, v1
	v_exp_f32_e32 v102, v96
	v_sub_f32_e32 v96, v107, v1
	v_add_f32_e32 v5, v9, v5
	v_exp_f32_e32 v103, v96
	v_sub_f32_e32 v96, v108, v1
	v_add_f32_e32 v5, v10, v5
	v_exp_f32_e32 v104, v96
	v_sub_f32_e32 v96, v109, v1
	v_cvt_pk_bf16_f32 v80, v207, v209
	v_cvt_pk_bf16_f32 v81, v210, v211
	v_cvt_pk_bf16_f32 v82, v212, v213
	v_cvt_pk_bf16_f32 v83, v214, v215
	v_add_f32_e32 v5, v11, v5
	v_exp_f32_e32 v105, v96
	v_sub_f32_e32 v96, v110, v1
	v_mfma_f32_32x32x16_bf16 v[32:47], v[222:225], v[80:83], v[32:47]
	v_lshl_add_u32 v84, v160, 1, v204
	v_add_f32_e32 v5, v99, v5
	v_exp_f32_e32 v106, v96
	v_sub_f32_e32 v96, v111, v1
	ds_read_b64 v[232:233], v84 offset:8192
	ds_read_b64 v[236:237], v84 offset:12288
	v_add_f32_e32 v5, v100, v5
	v_exp_f32_e32 v107, v96
	v_mfma_f32_32x32x16_bf16 v[16:31], v[226:229], v[80:83], v[16:31]
	v_lshl_add_u32 v80, v161, 1, v204
	ds_read_b64 v[230:231], v80 offset:8192
	ds_read_b64 v[234:235], v80 offset:12288
	v_cvt_pk_bf16_f32 v96, v4, v6
	v_cvt_pk_bf16_f32 v98, v9, v10
	v_cvt_pk_bf16_f32 v99, v11, v99
	v_add_f32_e32 v5, v101, v5
	v_add_f32_e32 v5, v102, v5
	v_mfma_f32_32x32x16_bf16 v[64:79], v[222:225], v[96:99], v[64:79]
	v_add_f32_e32 v5, v103, v5
	v_add_f32_e32 v5, v104, v5
	v_add_f32_e32 v5, v105, v5
	v_add_f32_e32 v5, v106, v5
	v_add_f32_e32 v5, v107, v5
	v_add_f32_e32 v3, v3, v5
	v_cvt_pk_bf16_f32 v4, v100, v101
	v_mfma_f32_32x32x16_bf16 v[48:63], v[226:229], v[96:99], v[48:63]
	s_waitcnt lgkmcnt(0)
	v_cvt_pk_bf16_f32 v5, v102, v103
	v_cvt_pk_bf16_f32 v6, v104, v105
	v_cvt_pk_bf16_f32 v7, v106, v107
	v_exp_f32_e32 v208, v8
	v_cvt_pk_bf16_f32 v8, v216, v217
	v_mfma_f32_32x32x16_bf16 v[64:79], v[230:233], v[4:7], v[64:79]
	v_cvt_pk_bf16_f32 v9, v218, v219
	v_cvt_pk_bf16_f32 v10, v220, v205
	v_cvt_pk_bf16_f32 v11, v206, v208
	v_mfma_f32_32x32x16_bf16 v[48:63], v[234:237], v[4:7], v[48:63]
	ds_read_b128 v[4:7], v13 offset:4096
	v_mfma_f32_32x32x16_bf16 v[32:47], v[230:233], v[8:11], v[32:47]
	v_mfma_f32_32x32x16_bf16 v[16:31], v[234:237], v[8:11], v[16:31]
	s_waitcnt lgkmcnt(0)
	v_mfma_f32_32x32x16_bf16 v[96:111], v[4:7], v[136:139], 0
	v_mfma_f32_32x32x16_bf16 v[80:95], v[4:7], v[140:143], 0
	ds_read_b128 v[4:7], v14 offset:4096
	s_waitcnt lgkmcnt(0)
	v_mfma_f32_32x32x16_bf16 v[96:111], v[4:7], v[124:127], v[96:111]
	v_mfma_f32_32x32x16_bf16 v[80:95], v[4:7], v[132:135], v[80:95]
	ds_read_b128 v[4:7], v15 offset:4096
	s_waitcnt lgkmcnt(0)
	v_mfma_f32_32x32x16_bf16 v[96:111], v[4:7], v[120:123], v[96:111]
	v_mfma_f32_32x32x16_bf16 v[80:95], v[4:7], v[128:131], v[80:95]
	ds_read_b128 v[4:7], v12 offset:4096
	s_waitcnt lgkmcnt(0)
	v_mfma_f32_32x32x16_bf16 v[96:111], v[4:7], v[112:115], v[96:111]
	v_mfma_f32_32x32x16_bf16 v[80:95], v[4:7], v[116:119], v[80:95]
	s_nop 10
	v_max_f32_e32 v4, v97, v97
	v_max_f32_e32 v5, v96, v96
	v_max_f32_e32 v4, v5, v4
	v_max3_f32 v4, v4, v98, v99
	v_max3_f32 v4, v4, v100, v101
	v_max3_f32 v4, v4, v102, v103
	v_max3_f32 v4, v4, v104, v105
	v_max3_f32 v4, v4, v106, v107
	v_max3_f32 v4, v4, v108, v109
	v_max3_f32 v4, v4, v110, v111
	ds_bpermute_b32 v5, v0, v4
	s_waitcnt lgkmcnt(0)
	v_max_f32_e32 v5, v5, v5
	v_max_f32_e32 v4, v4, v5
	v_add_f32_e32 v5, 0x41000000, v1
	v_cmp_gt_f32_e32 vcc, v4, v5
	s_cbranch_vccz .LBB0_234
	v_max_f32_e32 v4, v4, v4
	v_max_f32_e32 v5, v1, v1
	v_max_f32_e32 v5, v5, v4
	v_sub_f32_e32 v1, v1, v5
	v_exp_f32_e32 v4, v1
	v_mov_b32_e32 v1, v5
	v_mul_f32_e32 v3, v3, v4
	v_pk_mul_f32 v[78:79], v[78:79], v[4:5] op_sel_hi:[1,0]
	v_pk_mul_f32 v[76:77], v[76:77], v[4:5] op_sel_hi:[1,0]
	v_pk_mul_f32 v[74:75], v[74:75], v[4:5] op_sel_hi:[1,0]
	v_pk_mul_f32 v[72:73], v[72:73], v[4:5] op_sel_hi:[1,0]
	v_pk_mul_f32 v[70:71], v[70:71], v[4:5] op_sel_hi:[1,0]
	v_pk_mul_f32 v[68:69], v[68:69], v[4:5] op_sel_hi:[1,0]
	v_pk_mul_f32 v[66:67], v[66:67], v[4:5] op_sel_hi:[1,0]
	v_pk_mul_f32 v[64:65], v[64:65], v[4:5] op_sel_hi:[1,0]
	v_pk_mul_f32 v[62:63], v[62:63], v[4:5] op_sel_hi:[1,0]
	v_pk_mul_f32 v[60:61], v[60:61], v[4:5] op_sel_hi:[1,0]
	v_pk_mul_f32 v[58:59], v[58:59], v[4:5] op_sel_hi:[1,0]
	v_pk_mul_f32 v[56:57], v[56:57], v[4:5] op_sel_hi:[1,0]
	v_pk_mul_f32 v[54:55], v[54:55], v[4:5] op_sel_hi:[1,0]
	v_pk_mul_f32 v[52:53], v[52:53], v[4:5] op_sel_hi:[1,0]
	v_pk_mul_f32 v[50:51], v[50:51], v[4:5] op_sel_hi:[1,0]
	v_pk_mul_f32 v[48:49], v[48:49], v[4:5] op_sel_hi:[1,0]

.LBB0_240:
	v_sub_f32_e32 v4, v96, v1
	v_exp_f32_e32 v4, v4
	v_sub_f32_e32 v6, v97, v1
	v_exp_f32_e32 v6, v6
	v_sub_f32_e32 v7, v98, v1
	v_exp_f32_e32 v7, v7
	v_sub_f32_e32 v8, v99, v1
	v_exp_f32_e32 v8, v8
	v_sub_f32_e32 v9, v100, v1
	v_add_f32_e32 v5, 0, v4
	v_exp_f32_e32 v9, v9
	v_sub_f32_e32 v10, v101, v1
	v_add_f32_e32 v5, v6, v5
	v_exp_f32_e32 v10, v10
	v_sub_f32_e32 v11, v102, v1
	v_add_f32_e32 v5, v7, v5
	v_exp_f32_e32 v11, v11
	v_sub_f32_e32 v12, v103, v1
	v_add_f32_e32 v5, v8, v5
	v_exp_f32_e32 v99, v12
	v_sub_f32_e32 v12, v104, v1
	v_add_f32_e32 v5, v9, v5
	v_exp_f32_e32 v100, v12
	v_sub_f32_e32 v12, v105, v1
	v_add_f32_e32 v5, v10, v5
	v_exp_f32_e32 v101, v12
	v_sub_f32_e32 v12, v106, v1
	v_add_f32_e32 v5, v11, v5
	v_exp_f32_e32 v102, v12
	v_sub_f32_e32 v12, v107, v1
	v_add_f32_e32 v5, v99, v5
	v_exp_f32_e32 v103, v12
	v_sub_f32_e32 v12, v108, v1
	v_add_f32_e32 v5, v100, v5
	v_exp_f32_e32 v104, v12
	v_sub_f32_e32 v12, v109, v1
	v_add_f32_e32 v5, v101, v5
	v_exp_f32_e32 v105, v12
	v_sub_f32_e32 v12, v110, v1
	v_add_f32_e32 v5, v102, v5
	v_exp_f32_e32 v106, v12
	v_sub_f32_e32 v12, v111, v1
	v_add_f32_e32 v5, v103, v5
	v_exp_f32_e32 v107, v12
	v_add_f32_e32 v5, v104, v5
	v_add_f32_e32 v5, v105, v5
	v_add_f32_e32 v5, v106, v5
	v_add_f32_e32 v5, v107, v5
	v_add_f32_e32 v12, v3, v5
	v_sub_f32_e32 v3, v80, v159
	v_exp_f32_e32 v151, v3
	v_sub_f32_e32 v3, v81, v159
	v_exp_f32_e32 v153, v3
	v_sub_f32_e32 v3, v82, v159
	v_exp_f32_e32 v166, v3
	v_sub_f32_e32 v3, v83, v159
	v_exp_f32_e32 v167, v3
	v_sub_f32_e32 v3, v84, v159
	v_exp_f32_e32 v201, v3
	v_sub_f32_e32 v3, v85, v159
	v_exp_f32_e32 v202, v3
	v_sub_f32_e32 v3, v86, v159
	v_exp_f32_e32 v203, v3
	v_sub_f32_e32 v3, v87, v159
	v_exp_f32_e32 v204, v3
	v_sub_f32_e32 v3, v88, v159
	v_exp_f32_e32 v205, v3
	v_sub_f32_e32 v3, v89, v159
	v_exp_f32_e32 v206, v3
	v_sub_f32_e32 v3, v90, v159
	v_exp_f32_e32 v207, v3
	v_sub_f32_e32 v3, v91, v159
	v_exp_f32_e32 v208, v3
	v_sub_f32_e32 v3, v92, v159
	v_exp_f32_e32 v209, v3
	v_sub_f32_e32 v3, v93, v159
	v_exp_f32_e32 v149, v3
	v_sub_f32_e32 v3, v94, v159
	v_exp_f32_e32 v150, v3
	v_sub_f32_e32 v3, v95, v159
	v_exp_f32_e32 v152, v3
	v_lshl_add_u32 v3, v154, 1, v165
	v_lshl_add_u32 v84, v164, 1, v3
	v_lshl_add_u32 v88, v163, 1, v3
	ds_read_b64 v[222:223], v84 offset:8192
	ds_read_b64 v[226:227], v84 offset:12288
	ds_read_b64 v[224:225], v88 offset:8192
	ds_read_b64 v[228:229], v88 offset:12288
	v_cvt_pk_bf16_f32 v80, v151, v153
	v_cvt_pk_bf16_f32 v81, v166, v167
	v_cvt_pk_bf16_f32 v82, v201, v202
	s_waitcnt lgkmcnt(0)
	v_cvt_pk_bf16_f32 v83, v203, v204
	v_lshl_add_u32 v84, v160, 1, v3
	ds_read_b64 v[232:233], v84 offset:8192
	ds_read_b64 v[236:237], v84 offset:12288
	v_mfma_f32_32x32x16_bf16 v[32:47], v[222:225], v[80:83], v[32:47]
	v_cvt_pk_bf16_f32 v96, v4, v6
	v_cvt_pk_bf16_f32 v97, v7, v8
	v_cvt_pk_bf16_f32 v98, v9, v10
	v_cvt_pk_bf16_f32 v99, v11, v99
	v_cvt_pk_bf16_f32 v4, v100, v101
	v_cvt_pk_bf16_f32 v5, v102, v103
	v_cvt_pk_bf16_f32 v6, v104, v105
	v_mfma_f32_32x32x16_bf16 v[16:31], v[226:229], v[80:83], v[16:31]
	v_lshl_add_u32 v80, v161, 1, v3
	ds_read_b64 v[230:231], v80 offset:8192
	ds_read_b64 v[234:235], v80 offset:12288
	v_cvt_pk_bf16_f32 v7, v106, v107
	v_cvt_pk_bf16_f32 v8, v205, v206
	v_cvt_pk_bf16_f32 v9, v207, v208
	v_cvt_pk_bf16_f32 v10, v209, v149
	v_cvt_pk_bf16_f32 v11, v150, v152
	v_mfma_f32_32x32x16_bf16 v[64:79], v[222:225], v[96:99], v[64:79]
	v_mfma_f32_32x32x16_bf16 v[48:63], v[226:229], v[96:99], v[48:63]
	s_waitcnt lgkmcnt(0)
	v_mfma_f32_32x32x16_bf16 v[64:79], v[230:233], v[4:7], v[64:79]
	s_nop 0
	v_mfma_f32_32x32x16_bf16 v[48:63], v[234:237], v[4:7], v[48:63]
	ds_read_b128 v[4:7], v14 offset:4096
	v_mfma_f32_32x32x16_bf16 v[32:47], v[230:233], v[8:11], v[32:47]
	v_mfma_f32_32x32x16_bf16 v[16:31], v[234:237], v[8:11], v[16:31]
	s_waitcnt lgkmcnt(0)
	v_mfma_f32_32x32x16_bf16 v[96:111], v[4:7], v[136:139], 0
	v_mfma_f32_32x32x16_bf16 v[80:95], v[4:7], v[140:143], 0
	ds_read_b128 v[4:7], v15 offset:4096
	s_waitcnt lgkmcnt(0)
	v_mfma_f32_32x32x16_bf16 v[96:111], v[4:7], v[124:127], v[96:111]
	v_mfma_f32_32x32x16_bf16 v[80:95], v[4:7], v[132:135], v[80:95]
	ds_read_b128 v[4:7], v148 offset:4096
	s_waitcnt lgkmcnt(0)
	v_mfma_f32_32x32x16_bf16 v[96:111], v[4:7], v[120:123], v[96:111]
	v_mfma_f32_32x32x16_bf16 v[80:95], v[4:7], v[128:131], v[80:95]
	ds_read_b128 v[4:7], v13 offset:4096
	s_waitcnt lgkmcnt(0)
	v_mfma_f32_32x32x16_bf16 v[96:111], v[4:7], v[112:115], v[96:111]
	v_mfma_f32_32x32x16_bf16 v[80:95], v[4:7], v[116:119], v[80:95]
	s_nop 10
	v_max_f32_e32 v4, v97, v97
	v_max_f32_e32 v5, v96, v96
	v_max_f32_e32 v4, v5, v4
	v_max3_f32 v4, v4, v98, v99
	v_max3_f32 v4, v4, v100, v101
	v_max3_f32 v4, v4, v102, v103
	v_max3_f32 v4, v4, v104, v105
	v_max3_f32 v4, v4, v106, v107
	v_max3_f32 v4, v4, v108, v109
	v_max3_f32 v4, v4, v110, v111
	ds_bpermute_b32 v5, v0, v4
	s_waitcnt lgkmcnt(0)
	v_max_f32_e32 v5, v5, v5
	v_max_f32_e32 v4, v4, v5
	v_add_f32_e32 v5, 0x41000000, v1
	v_cmp_gt_f32_e32 vcc, v4, v5
	s_cbranch_vccz .LBB0_242
	v_max_f32_e32 v4, v4, v4
	v_max_f32_e32 v5, v1, v1
	v_max_f32_e32 v5, v5, v4
	v_sub_f32_e32 v1, v1, v5
	v_exp_f32_e32 v4, v1
	v_mov_b32_e32 v1, v5
	v_mul_f32_e32 v12, v12, v4
	v_pk_mul_f32 v[78:79], v[78:79], v[4:5] op_sel_hi:[1,0]
	v_pk_mul_f32 v[76:77], v[76:77], v[4:5] op_sel_hi:[1,0]
	v_pk_mul_f32 v[74:75], v[74:75], v[4:5] op_sel_hi:[1,0]
	v_pk_mul_f32 v[72:73], v[72:73], v[4:5] op_sel_hi:[1,0]
	v_pk_mul_f32 v[70:71], v[70:71], v[4:5] op_sel_hi:[1,0]
	v_pk_mul_f32 v[68:69], v[68:69], v[4:5] op_sel_hi:[1,0]
	v_pk_mul_f32 v[66:67], v[66:67], v[4:5] op_sel_hi:[1,0]
	v_pk_mul_f32 v[64:65], v[64:65], v[4:5] op_sel_hi:[1,0]
	v_pk_mul_f32 v[62:63], v[62:63], v[4:5] op_sel_hi:[1,0]
	v_pk_mul_f32 v[60:61], v[60:61], v[4:5] op_sel_hi:[1,0]
	v_pk_mul_f32 v[58:59], v[58:59], v[4:5] op_sel_hi:[1,0]
	v_pk_mul_f32 v[56:57], v[56:57], v[4:5] op_sel_hi:[1,0]
	v_pk_mul_f32 v[54:55], v[54:55], v[4:5] op_sel_hi:[1,0]
	v_pk_mul_f32 v[52:53], v[52:53], v[4:5] op_sel_hi:[1,0]
	v_pk_mul_f32 v[50:51], v[50:51], v[4:5] op_sel_hi:[1,0]
	v_pk_mul_f32 v[48:49], v[48:49], v[4:5] op_sel_hi:[1,0]
